# stack: attn compiler vmcnt(0) removed; LN1 router packed f32; MLA waves4-7 prio; UKV up-proj skips zero-padded K half; COMB expert loop software-pipelined via LDS-spilled buffer; MLA K fragments read
# speedup vs baseline: 1.0071x; 1.0071x over previous
.LBB0_513:
	s_cmp_eq_u32 s52, 0
	s_mov_b32 s9, 0x1fa00000
	s_cselect_b32 s9, s9, 0x20c00000
	s_mov_b32 s13, 0x1a00000
	s_cselect_b32 s15, s13, 0x1a80000
	s_add_u32 s9, s2, s9
	s_addc_u32 s20, s3, 0
	s_ashr_i32 s13, s12, 31
	s_lshl_b64 s[18:19], s[12:13], 17
	s_add_u32 s18, s9, s18
	s_addc_u32 s19, s20, s19
	s_and_b64 s[20:21], s[16:17], exec
	s_cselect_b32 s9, s19, s27
	s_cselect_b32 s13, s18, s26
	s_add_u32 s23, s48, s15
	s_addc_u32 s28, s49, 0
	s_ashr_i32 s15, s14, 31
	s_lshl_b64 s[20:21], s[14:15], 17
	s_add_u32 s20, s23, s20
	s_addc_u32 s21, s28, s21
	s_and_b64 s[28:29], s[16:17], exec
	v_mov_b32_e32 v10, 0
	s_mov_b32 s36, 0
	s_cselect_b32 s15, s21, s25
	s_cselect_b32 s53, s20, s24
	s_mov_b64 s[28:29], -1
	s_mov_b64 s[30:31], 0
	s_cmp_eq_u32 s51, 0
	s_cbranch_scc1 .Luq_two_trips
	s_mov_b64 s[28:29], 0
	s_mov_b64 s[30:31], -1
.Luq_two_trips:
	v_mov_b32_e32 v11, v10
	v_mov_b32_e32 v12, v10
	v_mov_b32_e32 v13, v10
	v_mov_b32_e32 v18, v10
	v_mov_b32_e32 v19, v10
	v_mov_b32_e32 v20, v10
	v_mov_b32_e32 v21, v10
	v_mov_b32_e32 v34, v10
	v_mov_b32_e32 v35, v10
	v_mov_b32_e32 v36, v10
	v_mov_b32_e32 v37, v10
	v_mov_b32_e32 v42, v10
	v_mov_b32_e32 v43, v10
	v_mov_b32_e32 v44, v10
	v_mov_b32_e32 v45, v10
	v_mov_b32_e32 v2, v10
	v_mov_b32_e32 v3, v10
	v_mov_b32_e32 v4, v10
	v_mov_b32_e32 v5, v10
	v_mov_b32_e32 v6, v10
	v_mov_b32_e32 v7, v10
	v_mov_b32_e32 v8, v10
	v_mov_b32_e32 v9, v10
	v_mov_b32_e32 v14, v10
	v_mov_b32_e32 v15, v10
	v_mov_b32_e32 v16, v10
	v_mov_b32_e32 v17, v10
	v_mov_b32_e32 v22, v10
	v_mov_b32_e32 v23, v10
	v_mov_b32_e32 v24, v10
	v_mov_b32_e32 v25, v10
	v_mov_b32_e32 v38, v10
	v_mov_b32_e32 v39, v10
	v_mov_b32_e32 v40, v10
	v_mov_b32_e32 v41, v10
	v_mov_b32_e32 v46, v10
	v_mov_b32_e32 v47, v10
	v_mov_b32_e32 v48, v10
	v_mov_b32_e32 v49, v10
	v_mov_b32_e32 v58, v10
	v_mov_b32_e32 v59, v10
	v_mov_b32_e32 v60, v10
	v_mov_b32_e32 v61, v10
	v_mov_b32_e32 v62, v10
	v_mov_b32_e32 v63, v10
	v_mov_b32_e32 v64, v10
	v_mov_b32_e32 v65, v10
	v_mov_b32_e32 v66, v10
	v_mov_b32_e32 v67, v10
	v_mov_b32_e32 v68, v10
	v_mov_b32_e32 v69, v10
	v_mov_b32_e32 v70, v10
	v_mov_b32_e32 v71, v10
	v_mov_b32_e32 v72, v10
	v_mov_b32_e32 v73, v10
	v_mov_b32_e32 v74, v10
	v_mov_b32_e32 v75, v10
	v_mov_b32_e32 v76, v10
	v_mov_b32_e32 v77, v10
	v_mov_b32_e32 v82, v10
	v_mov_b32_e32 v83, v10
	v_mov_b32_e32 v84, v10
	v_mov_b32_e32 v85, v10
	v_mov_b32_e32 v90, v10
	v_mov_b32_e32 v91, v10
	v_mov_b32_e32 v92, v10
	v_mov_b32_e32 v93, v10
	v_mov_b32_e32 v98, v10
	v_mov_b32_e32 v99, v10
	v_mov_b32_e32 v100, v10
	v_mov_b32_e32 v101, v10
	v_mov_b32_e32 v106, v10
	v_mov_b32_e32 v107, v10
	v_mov_b32_e32 v108, v10
	v_mov_b32_e32 v109, v10
	v_mov_b32_e32 v114, v10
	v_mov_b32_e32 v115, v10
	v_mov_b32_e32 v116, v10
	v_mov_b32_e32 v117, v10
	v_mov_b32_e32 v78, v10
	v_mov_b32_e32 v79, v10
	v_mov_b32_e32 v80, v10
	v_mov_b32_e32 v81, v10
	v_mov_b32_e32 v86, v10
	v_mov_b32_e32 v87, v10
	v_mov_b32_e32 v88, v10
	v_mov_b32_e32 v89, v10
	v_mov_b32_e32 v94, v10
	v_mov_b32_e32 v95, v10
	v_mov_b32_e32 v96, v10
	v_mov_b32_e32 v97, v10
	v_mov_b32_e32 v102, v10
	v_mov_b32_e32 v103, v10
	v_mov_b32_e32 v104, v10
	v_mov_b32_e32 v105, v10
	v_mov_b32_e32 v110, v10
	v_mov_b32_e32 v111, v10
	v_mov_b32_e32 v112, v10
	v_mov_b32_e32 v113, v10
	v_mov_b32_e32 v118, v10
	v_mov_b32_e32 v119, v10
	v_mov_b32_e32 v120, v10
	v_mov_b32_e32 v121, v10
	v_mov_b32_e32 v122, v10
	v_mov_b32_e32 v123, v10
	v_mov_b32_e32 v124, v10
	v_mov_b32_e32 v125, v10
	v_mov_b32_e32 v126, v10
	v_mov_b32_e32 v127, v10
	v_mov_b32_e32 v128, v10
	v_mov_b32_e32 v129, v10
	v_mov_b32_e32 v54, v10
	v_mov_b32_e32 v55, v10
	v_mov_b32_e32 v56, v10
	v_mov_b32_e32 v57, v10
	v_mov_b32_e32 v50, v10
	v_mov_b32_e32 v51, v10
	v_mov_b32_e32 v52, v10
	v_mov_b32_e32 v53, v10
	v_mov_b32_e32 v30, v10
	v_mov_b32_e32 v31, v10
	v_mov_b32_e32 v32, v10
	v_mov_b32_e32 v33, v10
	v_mov_b32_e32 v26, v10
	v_mov_b32_e32 v27, v10
	v_mov_b32_e32 v28, v10
	v_mov_b32_e32 v29, v10

.LBB0_658:
	s_lshl_b32 s55, s51, 6
	s_ashr_i32 s53, s51, 5
	s_and_b32 s55, s55, 0x600
	s_lshl_b32 s23, s53, 11
	s_add_i32 s55, s55, s0
	s_add_i32 s55, s55, s23
	s_mulk_i32 s54, 0xc0
	v_and_b32_e32 v12, 31, v0
	v_ashrrev_i32_e32 v154, 5, v0
	s_add_u32 s54, s37, s54
	v_or_b32_e32 v150, s55, v12
	s_addc_u32 s55, s38, 0
	v_lshlrev_b32_e32 v2, 3, v154
	v_ashrrev_i32_e32 v3, 31, v2
	v_mov_b64_e32 v[8:9], s[54:55]
	s_movk_i32 s23, 0x600
	v_mad_i64_i32 v[4:5], s[54:55], v150, s23, v[8:9]
	v_lshlrev_b64 v[10:11], 1, v[2:3]
	v_lshl_add_u64 v[2:3], v[4:5], 0, v[10:11]
	global_load_dwordx4 v[112:115], v[2:3], off
	global_load_dwordx4 v[116:119], v[2:3], off offset:32
	global_load_dwordx4 v[14:17], v[2:3], off offset:128
	global_load_dwordx4 v[120:123], v[2:3], off offset:64
	global_load_dwordx4 v[124:127], v[2:3], off offset:96
	v_lshlrev_b32_e32 v4, 7, v150
	v_and_b32_e32 v44, 0x3ef80, v4
	v_mbcnt_lo_u32_b32 v6, -1, 0
	v_mbcnt_hi_u32_b32 v6, -1, v6
	v_mbcnt_lo_u32_b32 v34, -1, 0
	v_mbcnt_hi_u32_b32 v34, -1, v34
	v_mbcnt_lo_u32_b32 v35, -1, 0
	v_mbcnt_hi_u32_b32 v35, -1, v35
	v_mbcnt_lo_u32_b32 v36, -1, 0
	v_mbcnt_hi_u32_b32 v36, -1, v36
	global_load_dwordx4 v[18:21], v44, s[4:5]
	global_load_dwordx4 v[22:25], v44, s[4:5] offset:32
	global_load_dwordx4 v[26:29], v44, s[4:5] offset:16
	global_load_dwordx4 v[30:33], v44, s[4:5] offset:48
	v_cmp_gt_u32_e32 vcc, 32, v0
	v_and_b32_e32 v37, 32, v6
	v_and_b32_e32 v39, 32, v34
	v_cndmask_b32_e64 v7, 1.0, -1.0, vcc
	v_cmp_eq_u32_e32 vcc, 0, v37
	v_and_b32_e32 v35, 32, v35
	v_and_b32_e32 v41, 32, v36
	global_load_dwordx4 v[2:5], v[2:3], off offset:160
	v_lshlrev_b32_e32 v13, 4, v0
	v_add_u32_e32 v155, s41, v13
	v_or_b32_e32 v152, 32, v150
	v_mad_i64_i32 v[8:9], s[54:55], v152, s23, v[8:9]
	s_lshl_b32 s23, s53, 8
	s_add_i32 s54, s23, 0x8000
	s_ashr_i32 s55, s54, 31
	s_lshl_b64 s[60:61], s[54:55], 11
	s_add_u32 s56, s1, s60
	s_addc_u32 s59, s8, s61
	s_lshl_b64 s[54:55], s[54:55], 6
	s_add_u32 s54, s39, s54
	s_addc_u32 s55, s40, s55
	v_ashrrev_i32_e32 v145, 31, v144
	s_mov_b32 m0, s47
	v_ashrrev_i32_e32 v147, 31, v146
	v_ashrrev_i32_e32 v149, 31, v148
	v_ashrrev_i32_e32 v151, 31, v150
	v_ashrrev_i32_e32 v153, 31, v152
	v_mov_b32_e32 v156, 0
	v_mov_b32_e32 v175, 0xf149f2ca
	v_mov_b32_e32 v176, 0xf149f2ca
	v_mov_b32_e32 v159, 0
	s_waitcnt vmcnt(0)
	v_mov_b32_e32 v43, v14
	v_mov_b32_e32 v45, v14
	v_mov_b32_e32 v46, v15
	v_mov_b32_e32 v47, v15
	v_permlane32_swap_b32_e32 v43, v45
	v_lshlrev_b32_e32 v36, 16, v15
	v_and_b32_e32 v38, 0xffff0000, v15
	v_permlane32_swap_b32_e32 v46, v47
	v_cndmask_b32_e32 v15, v43, v45, vcc
	v_cmp_eq_u32_e32 vcc, 0, v39
	v_mov_b32_e32 v48, v16
	v_mov_b32_e32 v49, v16
	v_lshlrev_b32_e32 v34, 16, v14
	v_mov_b32_e32 v6, v18
	v_lshlrev_b32_e32 v40, 16, v16
	v_and_b32_e32 v42, 0xffff0000, v16
	v_cndmask_b32_e32 v16, v46, v47, vcc
	v_cmp_eq_u32_e32 vcc, 0, v35
	v_lshlrev_b32_e32 v35, 16, v15
	v_and_b32_e32 v14, 0xffff0000, v14
	v_permlane32_swap_b32_e32 v48, v49
	v_and_b32_e32 v15, 0xffff0000, v15
	v_pk_mul_f32 v[34:35], v[6:7], v[34:35]
	v_mov_b32_e32 v6, v19
	v_cndmask_b32_e32 v18, v48, v49, vcc
	v_lshlrev_b32_e32 v37, 16, v16
	v_pk_mul_f32 v[14:15], v[6:7], v[14:15]
	v_mov_b32_e32 v6, v20
	v_cmp_eq_u32_e32 vcc, 0, v41
	v_and_b32_e32 v39, 0xffff0000, v16
	v_lshlrev_b32_e32 v41, 16, v18
	v_and_b32_e32 v43, 0xffff0000, v18
	v_pk_mul_f32 v[18:19], v[6:7], v[36:37]
	v_mov_b32_e32 v6, v21
	v_pk_mul_f32 v[20:21], v[6:7], v[38:39]
	v_mov_b32_e32 v6, v26
	v_mov_b32_e32 v50, v17
	v_mov_b32_e32 v51, v17
	v_fmac_f32_e32 v34, v35, v22
	v_fmac_f32_e32 v14, v15, v23
	v_fmac_f32_e32 v18, v19, v24
	v_pk_mul_f32 v[22:23], v[6:7], v[40:41]
	v_mov_b32_e32 v6, v27
	v_permlane32_swap_b32_e32 v50, v51
	v_fmac_f32_e32 v20, v21, v25
	v_cvt_pk_bf16_f32 v15, v18, v20
	v_pk_mul_f32 v[18:19], v[6:7], v[42:43]
	v_cndmask_b32_e32 v45, v50, v51, vcc
	v_fmac_f32_e32 v18, v19, v31
	v_fmac_f32_e32 v22, v23, v30
	v_cvt_pk_bf16_f32 v16, v22, v18
	v_lshlrev_b32_e32 v18, 16, v17
	v_lshlrev_b32_e32 v19, 16, v45
	v_mov_b32_e32 v6, v28
	v_pk_mul_f32 v[18:19], v[6:7], v[18:19]
	v_and_b32_e32 v21, 0xffff0000, v45
	v_and_b32_e32 v20, 0xffff0000, v17
	v_mov_b32_e32 v6, v29
	v_pk_mul_f32 v[20:21], v[6:7], v[20:21]
	v_cvt_pk_bf16_f32 v14, v34, v14
	v_fmac_f32_e32 v18, v32, v19
	v_fmac_f32_e32 v20, v33, v21
	v_cvt_pk_bf16_f32 v17, v18, v20
	ds_write_b128 v155, v[14:17]
	v_mov_b32_e32 v218, v14
	v_mov_b32_e32 v219, v15
	v_mov_b32_e32 v220, v16
	v_mov_b32_e32 v221, v17
	v_mbcnt_lo_u32_b32 v6, -1, 0
	v_mbcnt_hi_u32_b32 v6, -1, v6
	v_mbcnt_lo_u32_b32 v33, -1, 0
	v_mbcnt_hi_u32_b32 v33, -1, v33
	v_mbcnt_lo_u32_b32 v35, -1, 0
	v_mbcnt_hi_u32_b32 v35, -1, v35
	v_mbcnt_lo_u32_b32 v37, -1, 0
	v_mbcnt_hi_u32_b32 v37, -1, v37
	global_load_dwordx4 v[14:17], v44, s[4:5] offset:64
	global_load_dwordx4 v[18:21], v44, s[4:5] offset:96
	global_load_dwordx4 v[22:25], v44, s[4:5] offset:80
	global_load_dwordx4 v[26:29], v44, s[4:5] offset:112
	v_mov_b32_e32 v39, v2
	v_mov_b32_e32 v41, v2
	v_mov_b32_e32 v43, v3
	v_mov_b32_e32 v44, v3
	v_lshlrev_b32_e32 v34, 16, v3
	v_and_b32_e32 v36, 0xffff0000, v3
	v_and_b32_e32 v3, 32, v6
	v_mov_b32_e32 v45, v4
	v_mov_b32_e32 v46, v4
	v_lshlrev_b32_e32 v38, 16, v4
	v_and_b32_e32 v40, 0xffff0000, v4
	v_permlane32_swap_b32_e32 v39, v41
	v_and_b32_e32 v4, 32, v33
	v_cmp_eq_u32_e32 vcc, 0, v3
	v_permlane32_swap_b32_e32 v43, v44
	v_and_b32_e32 v6, 32, v35
	v_cndmask_b32_e32 v3, v39, v41, vcc
	v_cmp_eq_u32_e32 vcc, 0, v4
	v_permlane32_swap_b32_e32 v45, v46
	s_nop 0
	v_cndmask_b32_e32 v4, v43, v44, vcc
	v_cmp_eq_u32_e32 vcc, 0, v6
	v_and_b32_e32 v33, 32, v37
	v_lshlrev_b32_e32 v32, 16, v2
	v_cndmask_b32_e32 v6, v45, v46, vcc
	v_cmp_eq_u32_e32 vcc, 0, v33
	v_lshlrev_b32_e32 v33, 16, v3
	v_lshlrev_b32_e32 v39, 16, v6
	v_and_b32_e32 v41, 0xffff0000, v6
	v_and_b32_e32 v2, 0xffff0000, v2
	v_and_b32_e32 v3, 0xffff0000, v3
	v_lshlrev_b32_e32 v35, 16, v4
	v_and_b32_e32 v37, 0xffff0000, v4
	v_mov_b32_e32 v47, v5
	v_mov_b32_e32 v48, v5
	v_lshl_add_u64 v[30:31], v[8:9], 0, v[10:11]
	s_nop 0
	v_permlane32_swap_b32_e32 v47, v48
	global_load_dwordx4 v[8:11], v[30:31], off offset:128
	v_cndmask_b32_e32 v44, v47, v48, vcc
	v_lshlrev_b32_e32 v42, 16, v5
	v_lshlrev_b32_e32 v43, 16, v44
	s_waitcnt vmcnt(4)
	v_mov_b32_e32 v6, v14
	v_pk_mul_f32 v[32:33], v[6:7], v[32:33]
	v_mov_b32_e32 v6, v15
	v_pk_mul_f32 v[2:3], v[6:7], v[2:3]
	v_mov_b32_e32 v6, v16
	v_pk_mul_f32 v[14:15], v[6:7], v[34:35]
	v_mov_b32_e32 v6, v17
	v_pk_mul_f32 v[16:17], v[6:7], v[36:37]
	s_waitcnt vmcnt(2)
	v_mov_b32_e32 v6, v22
	v_fmac_f32_e32 v32, v33, v18
	v_fmac_f32_e32 v2, v3, v19
	v_fmac_f32_e32 v14, v15, v20
	v_pk_mul_f32 v[18:19], v[6:7], v[38:39]
	v_mov_b32_e32 v6, v23
	v_fmac_f32_e32 v16, v17, v21
	v_cvt_pk_bf16_f32 v3, v14, v16
	v_pk_mul_f32 v[14:15], v[6:7], v[40:41]
	v_mov_b32_e32 v6, v24
	s_waitcnt vmcnt(1)
	v_fmac_f32_e32 v14, v15, v27
	v_fmac_f32_e32 v18, v19, v26
	v_pk_mul_f32 v[16:17], v[6:7], v[42:43]
	v_cvt_pk_bf16_f32 v4, v18, v14
	v_and_b32_e32 v15, 0xffff0000, v44
	v_and_b32_e32 v14, 0xffff0000, v5
	v_mov_b32_e32 v6, v25
	v_cvt_pk_bf16_f32 v2, v32, v2
	v_pk_mul_f32 v[14:15], v[6:7], v[14:15]
	v_fmac_f32_e32 v16, v28, v17
	v_fmac_f32_e32 v14, v29, v15
	v_cvt_pk_bf16_f32 v5, v16, v14
	ds_write_b128 v155, v[2:5] offset:1024
	v_mov_b32_e32 v222, v2
	v_mov_b32_e32 v223, v3
	v_mov_b32_e32 v224, v4
	v_mov_b32_e32 v225, v5
	v_lshlrev_b32_e32 v2, 7, v152
	v_and_b32_e32 v44, 0x3ff80, v2
	global_load_dwordx4 v[128:131], v[30:31], off
	global_load_dwordx4 v[132:135], v[30:31], off offset:32
	global_load_dwordx4 v[136:139], v[30:31], off offset:64
	global_load_dwordx4 v[140:143], v[30:31], off offset:96
	v_mbcnt_lo_u32_b32 v6, -1, 0
	v_mbcnt_hi_u32_b32 v6, -1, v6
	v_mbcnt_lo_u32_b32 v27, -1, 0
	v_mbcnt_hi_u32_b32 v27, -1, v27
	v_mbcnt_lo_u32_b32 v29, -1, 0
	v_mbcnt_hi_u32_b32 v29, -1, v29
	v_mbcnt_lo_u32_b32 v33, -1, 0
	v_mbcnt_hi_u32_b32 v33, -1, v33
	global_load_dwordx4 v[2:5], v44, s[4:5]
	global_load_dwordx4 v[14:17], v44, s[4:5] offset:32
	global_load_dwordx4 v[18:21], v44, s[4:5] offset:16
	global_load_dwordx4 v[22:25], v44, s[4:5] offset:48
	v_and_b32_e32 v6, 32, v6
	v_and_b32_e32 v27, 32, v27
	v_cmp_eq_u32_e32 vcc, 0, v6
	v_and_b32_e32 v29, 32, v29
	s_waitcnt vmcnt(8)
	v_mov_b32_e32 v35, v8
	v_mov_b32_e32 v37, v8
	v_mov_b32_e32 v39, v9
	v_mov_b32_e32 v41, v9
	v_permlane32_swap_b32_e32 v35, v37
	s_nop 0
	v_permlane32_swap_b32_e32 v39, v41
	v_cndmask_b32_e32 v6, v35, v37, vcc
	v_cmp_eq_u32_e32 vcc, 0, v27
	v_mov_b32_e32 v43, v10
	v_mov_b32_e32 v45, v10
	v_mov_b32_e32 v46, v11
	v_mov_b32_e32 v47, v11
	v_lshlrev_b32_e32 v26, 16, v8
	v_and_b32_e32 v28, 0xffff0000, v8
	v_lshlrev_b32_e32 v32, 16, v9
	v_and_b32_e32 v34, 0xffff0000, v9
	v_lshlrev_b32_e32 v36, 16, v10
	v_and_b32_e32 v38, 0xffff0000, v10
	v_lshlrev_b32_e32 v40, 16, v11
	v_and_b32_e32 v42, 0xffff0000, v11
	global_load_dwordx4 v[8:11], v[30:31], off offset:160
	v_cndmask_b32_e32 v31, v39, v41, vcc
	v_cmp_eq_u32_e32 vcc, 0, v29
	v_lshlrev_b32_e32 v27, 16, v6
	v_and_b32_e32 v29, 0xffff0000, v6
	v_permlane32_swap_b32_e32 v43, v45
	v_and_b32_e32 v30, 32, v33
	v_lshlrev_b32_e32 v33, 16, v31
	v_cndmask_b32_e32 v39, v43, v45, vcc
	v_and_b32_e32 v35, 0xffff0000, v31
	v_permlane32_swap_b32_e32 v46, v47
	v_cmp_eq_u32_e32 vcc, 0, v30
	v_lshlrev_b32_e32 v37, 16, v39
	v_and_b32_e32 v39, 0xffff0000, v39
	v_cndmask_b32_e32 v30, v46, v47, vcc
	v_lshlrev_b32_e32 v41, 16, v30
	v_and_b32_e32 v43, 0xffff0000, v30
	s_waitcnt vmcnt(4)
	v_mov_b32_e32 v6, v2
	v_pk_mul_f32 v[26:27], v[6:7], v[26:27]
	v_mov_b32_e32 v6, v3
	v_pk_mul_f32 v[2:3], v[6:7], v[28:29]
	v_mov_b32_e32 v6, v4
	s_waitcnt vmcnt(3)
	v_fmac_f32_e32 v26, v27, v14
	v_fmac_f32_e32 v2, v3, v15
	v_pk_mul_f32 v[14:15], v[6:7], v[32:33]
	v_mov_b32_e32 v6, v5
	v_pk_mul_f32 v[4:5], v[6:7], v[34:35]
	s_waitcnt vmcnt(2)
	v_mov_b32_e32 v6, v18
	v_fmac_f32_e32 v14, v15, v16
	v_fmac_f32_e32 v4, v5, v17
	v_pk_mul_f32 v[16:17], v[6:7], v[36:37]
	v_mov_b32_e32 v6, v19
	v_cvt_pk_bf16_f32 v3, v14, v4
	v_pk_mul_f32 v[4:5], v[6:7], v[38:39]
	v_mov_b32_e32 v6, v20
	s_waitcnt vmcnt(1)
	v_fmac_f32_e32 v16, v17, v22
	v_fmac_f32_e32 v4, v5, v23
	v_pk_mul_f32 v[14:15], v[6:7], v[40:41]
	v_mov_b32_e32 v6, v21
	v_cvt_pk_bf16_f32 v4, v16, v4
	v_pk_mul_f32 v[16:17], v[6:7], v[42:43]
	v_cvt_pk_bf16_f32 v2, v26, v2
	v_fmac_f32_e32 v14, v24, v15
	v_fmac_f32_e32 v16, v25, v17
	v_cvt_pk_bf16_f32 v5, v14, v16
	ds_write_b128 v155, v[2:5] offset:2048
	v_mov_b32_e32 v226, v2
	v_mov_b32_e32 v227, v3
	v_mov_b32_e32 v228, v4
	v_mov_b32_e32 v229, v5
	v_mbcnt_lo_u32_b32 v6, -1, 0
	v_mbcnt_hi_u32_b32 v6, -1, v6
	v_mbcnt_lo_u32_b32 v27, -1, 0
	v_mbcnt_hi_u32_b32 v27, -1, v27
	v_mbcnt_lo_u32_b32 v29, -1, 0
	v_mbcnt_hi_u32_b32 v29, -1, v29
	v_mbcnt_lo_u32_b32 v31, -1, 0
	v_mbcnt_hi_u32_b32 v31, -1, v31
	global_load_dwordx4 v[2:5], v44, s[4:5] offset:64
	global_load_dwordx4 v[14:17], v44, s[4:5] offset:96
	global_load_dwordx4 v[18:21], v44, s[4:5] offset:80
	global_load_dwordx4 v[22:25], v44, s[4:5] offset:112
	s_waitcnt vmcnt(4)
	v_mov_b32_e32 v33, v8
	v_mov_b32_e32 v35, v8
	v_and_b32_e32 v6, 32, v6
	v_mov_b32_e32 v37, v9
	v_mov_b32_e32 v38, v9
	v_lshlrev_b32_e32 v28, 16, v9
	v_and_b32_e32 v30, 0xffff0000, v9
	v_permlane32_swap_b32_e32 v33, v35
	v_and_b32_e32 v9, 32, v27
	v_cmp_eq_u32_e32 vcc, 0, v6
	v_mov_b32_e32 v39, v10
	v_mov_b32_e32 v40, v10
	v_mov_b32_e32 v41, v11
	v_mov_b32_e32 v42, v11
	v_lshlrev_b32_e32 v34, 16, v11
	v_and_b32_e32 v36, 0xffff0000, v11
	v_permlane32_swap_b32_e32 v37, v38
	v_and_b32_e32 v11, 32, v29
	v_cndmask_b32_e32 v6, v33, v35, vcc
	v_cmp_eq_u32_e32 vcc, 0, v9
	v_permlane32_swap_b32_e32 v39, v40
	v_and_b32_e32 v27, 32, v31
	v_cndmask_b32_e32 v31, v37, v38, vcc
	v_cmp_eq_u32_e32 vcc, 0, v11
	v_lshlrev_b32_e32 v26, 16, v8
	v_and_b32_e32 v9, 0xffff0000, v6
	v_cndmask_b32_e32 v11, v39, v40, vcc
	v_cmp_eq_u32_e32 vcc, 0, v27
	v_lshlrev_b32_e32 v27, 16, v6
	v_and_b32_e32 v8, 0xffff0000, v8
	v_lshlrev_b32_e32 v29, 16, v31
	v_and_b32_e32 v31, 0xffff0000, v31
	v_lshlrev_b32_e32 v32, 16, v10
	v_permlane32_swap_b32_e32 v41, v42
	v_lshlrev_b32_e32 v33, 16, v11
	v_and_b32_e32 v10, 0xffff0000, v10
	v_cndmask_b32_e32 v37, v41, v42, vcc
	v_and_b32_e32 v11, 0xffff0000, v11
	v_lshlrev_b32_e32 v35, 16, v37
	v_and_b32_e32 v37, 0xffff0000, v37
	s_waitcnt vmcnt(3)
	v_mov_b32_e32 v6, v2
	v_pk_mul_f32 v[26:27], v[6:7], v[26:27]
	v_mov_b32_e32 v6, v3
	v_pk_mul_f32 v[2:3], v[6:7], v[8:9]
	v_mov_b32_e32 v6, v4
	v_pk_mul_f32 v[8:9], v[6:7], v[28:29]
	v_mov_b32_e32 v6, v5
	v_pk_mul_f32 v[4:5], v[6:7], v[30:31]
	s_waitcnt vmcnt(1)
	v_mov_b32_e32 v6, v18
	v_fmac_f32_e32 v26, v27, v14
	v_fmac_f32_e32 v2, v3, v15
	v_fmac_f32_e32 v4, v5, v17
	v_pk_mul_f32 v[14:15], v[6:7], v[32:33]
	v_mov_b32_e32 v6, v19
	v_fmac_f32_e32 v8, v9, v16
	v_cvt_pk_bf16_f32 v3, v8, v4
	v_pk_mul_f32 v[4:5], v[6:7], v[10:11]
	v_mov_b32_e32 v6, v20
	v_pk_mul_f32 v[8:9], v[6:7], v[34:35]
	v_mov_b32_e32 v6, v21
	s_waitcnt vmcnt(0)
	v_fmac_f32_e32 v4, v5, v23
	v_fmac_f32_e32 v8, v24, v9
	v_pk_mul_f32 v[6:7], v[6:7], v[36:37]
	v_cvt_pk_bf16_f32 v2, v26, v2
	v_fmac_f32_e32 v14, v15, v22
	v_cvt_pk_bf16_f32 v4, v14, v4
	v_fmac_f32_e32 v6, v25, v7
	v_cvt_pk_bf16_f32 v5, v8, v6
	v_mov_b32_e32 v8, s59
	v_mov_b32_e32 v9, s55
	v_mov_b32_e32 v10, s56
	v_mov_b32_e32 v11, s54
	ds_write_b128 v155, v[2:5] offset:3072
	v_mov_b32_e32 v244, v2
	v_mov_b32_e32 v245, v3
	v_mov_b32_e32 v246, v4
	v_mov_b32_e32 v247, v5
	v_cndmask_b32_e64 v3, v8, v9, s[26:27]
	v_cndmask_b32_e64 v2, v10, v11, s[26:27]
	v_lshlrev_b64 v[4:5], 1, v[144:145]
	v_lshl_add_u64 v[2:3], v[2:3], 0, v[4:5]
	global_load_lds_dwordx4 v[2:3], off
	v_cndmask_b32_e64 v3, v8, v9, s[28:29]
	v_cndmask_b32_e64 v2, v10, v11, s[28:29]
	v_lshlrev_b64 v[6:7], 1, v[146:147]
	s_add_i32 s54, s23, 0x8040
	v_lshl_add_u64 v[2:3], v[2:3], 0, v[6:7]
	s_mov_b32 m0, s48
	s_ashr_i32 s55, s54, 31
	global_load_lds_dwordx4 v[2:3], off
	s_add_i32 m0, s42, s35
	s_lshl_b64 s[60:61], s[54:55], 11
	s_add_u32 s23, s1, s60
	s_addc_u32 s35, s8, s61
	s_lshl_b64 s[54:55], s[54:55], 6
	s_add_u32 s54, s39, s54
	v_cndmask_b32_e64 v3, v8, v9, s[30:31]
	v_cndmask_b32_e64 v2, v10, v11, s[30:31]
	v_lshlrev_b64 v[8:9], 1, v[148:149]
	s_addc_u32 s55, s40, s55
	v_lshl_add_u64 v[2:3], v[2:3], 0, v[8:9]
	v_mov_b32_e32 v10, s35
	v_mov_b32_e32 v11, s55
	v_mov_b32_e32 v14, s23
	v_mov_b32_e32 v15, s54
	global_load_lds_dwordx4 v[2:3], off
	v_cndmask_b32_e64 v3, v10, v11, s[26:27]
	v_cndmask_b32_e64 v2, v14, v15, s[26:27]
	v_lshl_add_u64 v[2:3], v[2:3], 0, v[4:5]
	s_mov_b32 m0, s49
	v_lshlrev_b32_e32 v4, 4, v154
	global_load_lds_dwordx4 v[2:3], off
	v_cndmask_b32_e64 v3, v10, v11, s[28:29]
	v_cndmask_b32_e64 v2, v14, v15, s[28:29]
	v_lshl_add_u64 v[2:3], v[2:3], 0, v[6:7]
	s_mov_b32 m0, s50
	v_and_b32_e32 v5, 0xc0, v13
	global_load_lds_dwordx4 v[2:3], off
	v_cndmask_b32_e64 v3, v10, v11, s[30:31]
	v_cndmask_b32_e64 v2, v14, v15, s[30:31]
	v_lshl_add_u64 v[2:3], v[2:3], 0, v[8:9]
	s_add_i32 m0, s42, s34
	v_lshlrev_b32_e32 v6, 8, v154
	global_load_lds_dwordx4 v[2:3], off
	v_lshlrev_b32_e32 v3, 1, v0
	v_mul_u32_u24_e32 v2, 0xd0, v12
	v_and_b32_e32 v3, 32, v3
	v_lshlrev_b32_e32 v0, 3, v0
	v_and_b32_e32 v0, 24, v0
	v_add3_u32 v157, 0, v2, v4
	v_add3_u32 v2, 0, v3, v5
	v_mov_b32_e32 v14, v1
	v_mov_b32_e32 v15, v1
	v_add3_u32 v158, v2, v0, v6
	v_mov_b32_e32 v0, v1
	v_mov_b32_e32 v2, v1
	v_mov_b32_e32 v3, v1
	v_mov_b32_e32 v4, v1
	v_mov_b32_e32 v5, v1
	v_mov_b32_e32 v6, v1
	v_mov_b32_e32 v7, v1
	v_mov_b32_e32 v8, v1
	v_mov_b32_e32 v9, v1
	v_mov_b32_e32 v10, v1
	v_mov_b32_e32 v11, v1
	v_mov_b32_e32 v12, v1
	v_mov_b32_e32 v13, v1
	v_mov_b64_e32 v[30:31], v[14:15]
	v_mov_b64_e32 v[46:47], v[14:15]
	v_mov_b64_e32 v[62:63], v[14:15]
	v_mov_b64_e32 v[78:79], v[14:15]
	s_mov_b32 s54, 0
	s_mov_b32 s55, 2
	s_movk_i32 s59, 0x80
	v_mov_b64_e32 v[28:29], v[12:13]
	v_mov_b64_e32 v[26:27], v[10:11]
	v_mov_b64_e32 v[24:25], v[8:9]
	v_mov_b64_e32 v[22:23], v[6:7]
	v_mov_b64_e32 v[20:21], v[4:5]
	v_mov_b64_e32 v[18:19], v[2:3]
	v_mov_b64_e32 v[16:17], v[0:1]
	v_mov_b64_e32 v[44:45], v[12:13]
	v_mov_b64_e32 v[42:43], v[10:11]
	v_mov_b64_e32 v[40:41], v[8:9]
	v_mov_b64_e32 v[38:39], v[6:7]
	v_mov_b64_e32 v[36:37], v[4:5]
	v_mov_b64_e32 v[34:35], v[2:3]
	v_mov_b64_e32 v[32:33], v[0:1]
	v_mov_b64_e32 v[60:61], v[12:13]
	v_mov_b64_e32 v[58:59], v[10:11]
	v_mov_b64_e32 v[56:57], v[8:9]
	v_mov_b64_e32 v[54:55], v[6:7]
	v_mov_b64_e32 v[52:53], v[4:5]
	v_mov_b64_e32 v[50:51], v[2:3]
	v_mov_b64_e32 v[48:49], v[0:1]
	s_mov_b32 s60, 0
	v_mov_b64_e32 v[76:77], v[12:13]
	v_mov_b64_e32 v[74:75], v[10:11]
	v_mov_b64_e32 v[72:73], v[8:9]
	v_mov_b64_e32 v[70:71], v[6:7]
	v_mov_b64_e32 v[68:69], v[4:5]
	v_mov_b64_e32 v[66:67], v[2:3]
	v_mov_b64_e32 v[64:65], v[0:1]
	s_branch .LBB0_660

.LBB0_666:
	s_mul_i32 s23, s54, 0x3400
	v_add_u32_e32 v193, s23, v157
	ds_read_b128 v[2:5], v193
	ds_read_b128 v[6:9], v193 offset:32
	ds_read_b128 v[10:13], v193 offset:64
	ds_read_b128 v[160:163], v193 offset:96
	ds_read_b128 v[164:167], v193 offset:128
	ds_read_b128 v[168:171], v193 offset:160
	s_waitcnt lgkmcnt(5)
	v_mfma_f32_32x32x16_bf16 v[96:111], v[2:5], v[112:115], 0
	s_waitcnt lgkmcnt(4)
	v_mfma_f32_32x32x16_bf16 v[96:111], v[6:9], v[116:119], v[96:111]
	s_waitcnt lgkmcnt(3)
	v_mfma_f32_32x32x16_bf16 v[96:111], v[10:13], v[120:123], v[96:111]
	s_waitcnt lgkmcnt(2)
	v_mfma_f32_32x32x16_bf16 v[96:111], v[160:163], v[124:127], v[96:111]
	s_waitcnt lgkmcnt(1)
	v_mfma_f32_32x32x16_bf16 v[96:111], v[164:167], v[218:221], v[96:111]
	s_waitcnt lgkmcnt(0)
	v_mfma_f32_32x32x16_bf16 v[96:111], v[168:171], v[222:225], v[96:111]
	s_nop 7
	s_waitcnt lgkmcnt(0)
	v_mfma_f32_32x32x16_bf16 v[80:95], v[2:5], v[128:131], 0
	s_nop 1
	v_max3_f32 v0, v96, s62, v97
	v_max3_f32 v0, v0, v98, v99
	v_max3_f32 v0, v0, v100, v101
	v_max3_f32 v0, v0, v102, v103
	v_max3_f32 v0, v0, v104, v105
	v_max3_f32 v0, v0, v106, v107
	v_max3_f32 v0, v0, v108, v109
	v_max3_f32 v0, v0, v110, v111
	v_mov_b32_e32 v2, v0
	s_nop 1
	v_permlane32_swap_b32_e32 v0, v2
	v_max_f32_e32 v2, v2, v2
	v_max_f32_e32 v0, v0, v0
	v_max_f32_e32 v0, v0, v2
	v_mul_f32_e32 v0, 0x3e16c740, v0
	v_mfma_f32_32x32x16_bf16 v[80:95], v[6:9], v[132:135], v[80:95]
	v_add_f32_e32 v2, 0x41000000, v176
	v_cmp_gt_f32_e32 vcc, v0, v2
	s_nop 1
	v_cndmask_b32_e32 v196, v176, v0, vcc
	v_sub_f32_e32 v0, v176, v196
	v_fma_f32 v2, v96, s63, -v196
	v_fma_f32 v3, v97, s63, -v196
	v_fma_f32 v4, v98, s63, -v196
	v_fma_f32 v5, v99, s63, -v196
	v_fma_f32 v6, v100, s63, -v196
	v_fma_f32 v7, v101, s63, -v196
	v_fma_f32 v8, v102, s63, -v196
	v_fma_f32 v9, v103, s63, -v196
	v_fma_f32 v14, v104, s63, -v196
	v_fma_f32 v96, v105, s63, -v196
	v_mfma_f32_32x32x16_bf16 v[80:95], v[10:13], v[136:139], v[80:95]
	v_fma_f32 v97, v106, s63, -v196
	v_fma_f32 v10, v107, s63, -v196
	v_fma_f32 v11, v108, s63, -v196
	v_fma_f32 v12, v109, s63, -v196
	v_fma_f32 v13, v110, s63, -v196
	v_fma_f32 v98, v111, s63, -v196
	v_exp_f32_e32 v0, v0
	v_mfma_f32_32x32x16_bf16 v[80:95], v[160:163], v[140:143], v[80:95]
	v_exp_f32_e32 v15, v2
	v_exp_f32_e32 v162, v3
	v_exp_f32_e32 v160, v4
	v_exp_f32_e32 v163, v5
	v_exp_f32_e32 v161, v6
	v_exp_f32_e32 v172, v10
	v_exp_f32_e32 v173, v12
	v_mfma_f32_32x32x16_bf16 v[80:95], v[164:167], v[226:229], v[80:95]
	v_exp_f32_e32 v165, v7
	v_exp_f32_e32 v164, v8
	v_exp_f32_e32 v166, v9
	v_exp_f32_e32 v167, v14
	v_exp_f32_e32 v174, v98
	v_cvt_pk_bf16_f32 v104, v15, v162
	v_cvt_pk_bf16_f32 v105, v160, v163
	v_mfma_f32_32x32x16_bf16 v[80:95], v[168:171], v[244:247], v[80:95]
	v_exp_f32_e32 v171, v96
	v_exp_f32_e32 v168, v97
	v_exp_f32_e32 v169, v11
	v_exp_f32_e32 v170, v13
	v_cvt_pk_bf16_f32 v106, v161, v165
	v_cvt_pk_bf16_f32 v107, v164, v166
	v_cvt_pk_bf16_f32 v2, v167, v171
	v_cvt_pk_bf16_f32 v3, v168, v172
	v_cvt_pk_bf16_f32 v4, v169, v173
	v_cvt_pk_bf16_f32 v5, v170, v174
	v_cmp_eq_f32_e32 vcc, 1.0, v0
	s_cmp_eq_u64 vcc, exec
	s_cbranch_scc1 .LBB0_668
	v_pk_mul_f32 v[78:79], v[78:79], v[0:1] op_sel_hi:[1,0]
	v_pk_mul_f32 v[76:77], v[76:77], v[0:1] op_sel_hi:[1,0]
	v_pk_mul_f32 v[74:75], v[74:75], v[0:1] op_sel_hi:[1,0]
	v_pk_mul_f32 v[72:73], v[72:73], v[0:1] op_sel_hi:[1,0]
	v_pk_mul_f32 v[70:71], v[70:71], v[0:1] op_sel_hi:[1,0]
	v_pk_mul_f32 v[68:69], v[68:69], v[0:1] op_sel_hi:[1,0]
	v_pk_mul_f32 v[66:67], v[66:67], v[0:1] op_sel_hi:[1,0]
	v_pk_mul_f32 v[64:65], v[64:65], v[0:1] op_sel_hi:[1,0]
	v_pk_mul_f32 v[62:63], v[62:63], v[0:1] op_sel_hi:[1,0]
	v_pk_mul_f32 v[60:61], v[60:61], v[0:1] op_sel_hi:[1,0]
	v_pk_mul_f32 v[58:59], v[58:59], v[0:1] op_sel_hi:[1,0]
	v_pk_mul_f32 v[56:57], v[56:57], v[0:1] op_sel_hi:[1,0]
	v_pk_mul_f32 v[54:55], v[54:55], v[0:1] op_sel_hi:[1,0]
	v_pk_mul_f32 v[52:53], v[52:53], v[0:1] op_sel_hi:[1,0]
	v_pk_mul_f32 v[50:51], v[50:51], v[0:1] op_sel_hi:[1,0]
	v_pk_mul_f32 v[48:49], v[48:49], v[0:1] op_sel_hi:[1,0]

.LBB0_670:
	ds_read_b128 v[2:5], v193 offset:6656
	s_nop 0
	v_mfma_f32_32x32x16_bf16 v[16:31], v[100:103], v[80:83], v[16:31]
	v_mfma_f32_32x32x16_bf16 v[32:47], v[6:9], v[80:83], v[32:47]
	v_mfma_f32_32x32x16_bf16 v[16:31], v[96:99], v[84:87], v[16:31]
	v_mfma_f32_32x32x16_bf16 v[32:47], v[10:13], v[84:87], v[32:47]
	ds_read_b128 v[6:9], v193 offset:6688
	ds_read_b128 v[10:13], v193 offset:6720
	ds_read_b128 v[198:201], v193 offset:6752
	ds_read_b128 v[202:205], v193 offset:6784
	ds_read_b128 v[210:213], v193 offset:6816
	s_waitcnt lgkmcnt(5)
	v_mfma_f32_32x32x16_bf16 v[96:111], v[2:5], v[112:115], 0
	s_waitcnt lgkmcnt(4)
	v_mfma_f32_32x32x16_bf16 v[96:111], v[6:9], v[116:119], v[96:111]
	s_waitcnt lgkmcnt(3)
	v_mfma_f32_32x32x16_bf16 v[96:111], v[10:13], v[120:123], v[96:111]
	s_waitcnt lgkmcnt(2)
	v_mfma_f32_32x32x16_bf16 v[96:111], v[198:201], v[124:127], v[96:111]
	s_waitcnt lgkmcnt(1)
	v_mfma_f32_32x32x16_bf16 v[96:111], v[202:205], v[218:221], v[96:111]
	s_waitcnt lgkmcnt(0)
	v_mfma_f32_32x32x16_bf16 v[96:111], v[210:213], v[222:225], v[96:111]
	s_nop 7
	s_waitcnt lgkmcnt(4)
	v_mfma_f32_32x32x16_bf16 v[80:95], v[2:5], v[128:131], 0
	s_nop 1
	v_max3_f32 v2, v96, s62, v97
	v_max3_f32 v2, v2, v98, v99
	v_max3_f32 v2, v2, v100, v101
	v_max3_f32 v2, v2, v102, v103
	v_max3_f32 v2, v2, v104, v105
	v_max3_f32 v2, v2, v106, v107
	v_max3_f32 v2, v2, v108, v109
	v_max3_f32 v2, v2, v110, v111
	v_mov_b32_e32 v3, v2
	s_nop 1
	v_permlane32_swap_b32_e32 v2, v3
	v_max_f32_e32 v3, v3, v3
	v_max_f32_e32 v2, v2, v2
	v_max_f32_e32 v2, v2, v3
	v_mul_f32_e32 v2, 0x3e16c740, v2
	s_waitcnt lgkmcnt(3)
	v_mfma_f32_32x32x16_bf16 v[80:95], v[6:9], v[132:135], v[80:95]
	v_add_f32_e32 v3, 0x41000000, v196
	v_cmp_gt_f32_e32 vcc, v2, v3
	s_nop 1
	v_cndmask_b32_e32 v176, v196, v2, vcc
	v_sub_f32_e32 v2, v196, v176
	v_fma_f32 v3, v96, s63, -v176
	v_fma_f32 v4, v97, s63, -v176
	v_fma_f32 v5, v98, s63, -v176
	v_fma_f32 v6, v99, s63, -v176
	v_fma_f32 v7, v100, s63, -v176
	v_fma_f32 v8, v101, s63, -v176
	v_fma_f32 v9, v102, s63, -v176
	v_fma_f32 v96, v103, s63, -v176
	v_fma_f32 v97, v104, s63, -v176
	v_fma_f32 v98, v105, s63, -v176
	s_waitcnt lgkmcnt(2)
	v_mfma_f32_32x32x16_bf16 v[80:95], v[10:13], v[136:139], v[80:95]
	v_fma_f32 v99, v106, s63, -v176
	v_fma_f32 v10, v107, s63, -v176
	v_fma_f32 v11, v108, s63, -v176
	v_fma_f32 v12, v109, s63, -v176
	v_fma_f32 v13, v110, s63, -v176
	v_fma_f32 v100, v111, s63, -v176
	v_exp_f32_e32 v108, v2
	v_mfma_f32_32x32x16_bf16 v[80:95], v[198:201], v[140:143], v[80:95]
	v_exp_f32_e32 v109, v7
	v_exp_f32_e32 v193, v8
	v_exp_f32_e32 v111, v9
	v_exp_f32_e32 v196, v96
	v_exp_f32_e32 v201, v97
	v_exp_f32_e32 v197, v11
	v_exp_f32_e32 v199, v12
	v_mfma_f32_32x32x16_bf16 v[80:95], v[202:205], v[226:229], v[80:95]
	v_exp_f32_e32 v205, v3
	v_exp_f32_e32 v207, v4
	v_exp_f32_e32 v206, v5
	v_exp_f32_e32 v208, v6
	v_exp_f32_e32 v203, v98
	v_exp_f32_e32 v202, v99
	v_exp_f32_e32 v204, v10
	s_waitcnt lgkmcnt(0)
	v_mfma_f32_32x32x16_bf16 v[80:95], v[210:213], v[244:247], v[80:95]
	v_exp_f32_e32 v198, v13
	v_exp_f32_e32 v200, v100
	v_cvt_pk_bf16_f32 v104, v205, v207
	v_cvt_pk_bf16_f32 v105, v206, v208
	v_cvt_pk_bf16_f32 v106, v109, v193
	v_cvt_pk_bf16_f32 v107, v111, v196
	v_cvt_pk_bf16_f32 v100, v201, v203
	v_cvt_pk_bf16_f32 v101, v202, v204
	v_cvt_pk_bf16_f32 v102, v197, v199
	v_cvt_pk_bf16_f32 v103, v198, v200
	v_cmp_eq_f32_e32 vcc, 1.0, v108
	s_cmp_eq_u64 vcc, exec
	s_cbranch_scc1 .LBB0_672
	v_pk_mul_f32 v[78:79], v[78:79], v[108:109] op_sel_hi:[1,0]
	v_pk_mul_f32 v[76:77], v[76:77], v[108:109] op_sel_hi:[1,0]
	v_pk_mul_f32 v[74:75], v[74:75], v[108:109] op_sel_hi:[1,0]
	v_pk_mul_f32 v[72:73], v[72:73], v[108:109] op_sel_hi:[1,0]
	v_pk_mul_f32 v[70:71], v[70:71], v[108:109] op_sel_hi:[1,0]
	v_pk_mul_f32 v[68:69], v[68:69], v[108:109] op_sel_hi:[1,0]
	v_pk_mul_f32 v[66:67], v[66:67], v[108:109] op_sel_hi:[1,0]
	v_pk_mul_f32 v[64:65], v[64:65], v[108:109] op_sel_hi:[1,0]
	v_pk_mul_f32 v[62:63], v[62:63], v[108:109] op_sel_hi:[1,0]
	v_pk_mul_f32 v[60:61], v[60:61], v[108:109] op_sel_hi:[1,0]
	v_pk_mul_f32 v[58:59], v[58:59], v[108:109] op_sel_hi:[1,0]
	v_pk_mul_f32 v[56:57], v[56:57], v[108:109] op_sel_hi:[1,0]
	v_pk_mul_f32 v[54:55], v[54:55], v[108:109] op_sel_hi:[1,0]
	v_pk_mul_f32 v[52:53], v[52:53], v[108:109] op_sel_hi:[1,0]
	v_pk_mul_f32 v[50:51], v[50:51], v[108:109] op_sel_hi:[1,0]
	v_pk_mul_f32 v[48:49], v[48:49], v[108:109] op_sel_hi:[1,0]

.LBB0_1624:
	v_cmp_lt_i32_e32 vcc, -1, v242
	s_and_b32 s28, vcc_lo, 0xffff
	s_lshr_b32 s29, vcc_lo, 16
	s_or_b32 s4, s28, s29
	s_cmp_eq_u32 s4, 0
	s_cbranch_scc1 .LBB0_1627
	v_mov_b32_e32 v202, 0
	s_ashr_i32 s30, s27, 31
	v_mov_b32_e32 v203, v202
	v_mov_b32_e32 v200, v202
	v_mov_b32_e32 v201, v202
	v_mov_b32_e32 v210, v202
	v_mov_b32_e32 v211, v202
	v_mov_b32_e32 v208, v202
	v_mov_b32_e32 v209, v202
	v_mov_b32_e32 v218, v202
	v_mov_b32_e32 v219, v202
	v_mov_b32_e32 v216, v202
	v_mov_b32_e32 v217, v202
	v_mov_b32_e32 v226, v202
	v_mov_b32_e32 v227, v202
	v_mov_b32_e32 v224, v202
	v_mov_b32_e32 v225, v202
	v_mov_b32_e32 v198, v202
	v_mov_b32_e32 v199, v202
	v_mov_b32_e32 v196, v202
	v_mov_b32_e32 v197, v202
	v_mov_b32_e32 v206, v202
	v_mov_b32_e32 v207, v202
	v_mov_b32_e32 v204, v202
	v_mov_b32_e32 v205, v202
	v_mov_b32_e32 v214, v202
	v_mov_b32_e32 v215, v202
	v_mov_b32_e32 v212, v202
	v_mov_b32_e32 v213, v202
	v_mov_b32_e32 v222, v202
	v_mov_b32_e32 v223, v202
	v_mov_b32_e32 v220, v202
	v_mov_b32_e32 v221, v202
	v_mbcnt_lo_u32_b32 v254, -1, 0
	v_mbcnt_hi_u32_b32 v254, -1, v254
	v_readlane_b32 s79, v255, 11
	s_nop 1
	s_lshl_b32 s79, s79, 6
	v_add_lshl_u32 v254, v254, s79, 4
	ds_write_b128 v254, v[170:173]
	ds_write_b128 v254, v[174:177] offset:8192
	ds_write_b128 v254, v[178:181] offset:16384
	ds_write_b128 v254, v[182:185] offset:24576
	s_waitcnt lgkmcnt(0)
	s_ff1_i32_b32 s68, s28
	s_ff1_i32_b32 s69, s29
	s_cmp_eq_u32 s28, 0
	s_cselect_b32 s68, 0, s68
	s_cselect_b64 s[70:71], -1, 0
	s_cmp_eq_u32 s29, 0
	s_cselect_b32 s69, 0, s69
	s_cselect_b64 s[72:73], -1, 0
	s_add_i32 s74, s69, 16
	s_nop 1
	v_readlane_b32 s75, v243, s68
	v_readlane_b32 s76, v242, s68
	v_readlane_b32 s77, v242, s74
	v_readlane_b32 s78, v243, s74
	s_mulk_i32 s68, 0x1200
	s_mulk_i32 s69, 0x1200
	v_mov_b32_e32 v230, s75
	v_mov_b32_e32 v228, s78
	s_cmp_eq_u32 s28, 0
	s_cselect_b32 s76, 0, s76
	s_cmp_eq_u32 s29, 0
	s_cselect_b32 s77, 0, s77
	v_cndmask_b32_e64 v230, v230, 0, s[70:71]
	v_cndmask_b32_e64 v228, v228, 0, s[72:73]
	s_add_i32 s50, s68, s27
	s_add_i32 s50, s50, s76
	s_lshl_b32 s50, s50, 11
	s_mov_b32 s51, 0
	s_add_i32 s54, s69, s27
	s_add_i32 s54, s54, s77
	s_lshl_b32 s54, s54, 11
	s_mov_b32 s55, 0
	v_lshl_add_u64 v[248:249], v[192:193], 0, s[50:51]
	global_load_dwordx4 v[166:169], v[248:249], off
	global_load_dwordx4 v[162:165], v[248:249], off offset:1024
	v_lshl_add_u64 v[248:249], v[192:193], 0, s[54:55]
	global_load_dwordx4 v[158:161], v[248:249], off
	global_load_dwordx4 v[154:157], v[248:249], off offset:1024
	s_add_i32 s79, s28, -1
	s_and_b32 s28, s28, s79
	s_add_i32 s79, s29, -1
	s_and_b32 s29, s29, s79
.Lcmb_loop:
	s_or_b32 s79, s28, s29
	s_cmp_eq_u32 s79, 0
	s_cbranch_scc1 .Lcmb_last0
	s_ff1_i32_b32 s68, s28
	s_ff1_i32_b32 s69, s29
	s_cmp_eq_u32 s28, 0
	s_cselect_b32 s68, 0, s68
	s_cselect_b64 s[70:71], -1, 0
	s_cmp_eq_u32 s29, 0
	s_cselect_b32 s69, 0, s69
	s_cselect_b64 s[72:73], -1, 0
	s_add_i32 s74, s69, 16
	s_nop 1
	v_readlane_b32 s75, v243, s68
	v_readlane_b32 s76, v242, s68
	v_readlane_b32 s77, v242, s74
	v_readlane_b32 s78, v243, s74
	s_mulk_i32 s68, 0x1200
	s_mulk_i32 s69, 0x1200
	v_mov_b32_e32 v250, s75
	v_mov_b32_e32 v252, s78
	s_cmp_eq_u32 s28, 0
	s_cselect_b32 s76, 0, s76
	s_cmp_eq_u32 s29, 0
	s_cselect_b32 s77, 0, s77
	v_cndmask_b32_e64 v250, v250, 0, s[70:71]
	v_cndmask_b32_e64 v252, v252, 0, s[72:73]
	s_add_i32 s50, s68, s27
	s_add_i32 s50, s50, s76
	s_lshl_b32 s50, s50, 11
	s_mov_b32 s51, 0
	s_add_i32 s54, s69, s27
	s_add_i32 s54, s54, s77
	s_lshl_b32 s54, s54, 11
	s_mov_b32 s55, 0
	v_lshl_add_u64 v[248:249], v[192:193], 0, s[50:51]
	global_load_dwordx4 v[182:185], v[248:249], off
	global_load_dwordx4 v[178:181], v[248:249], off offset:1024
	v_lshl_add_u64 v[248:249], v[192:193], 0, s[54:55]
	global_load_dwordx4 v[174:177], v[248:249], off
	global_load_dwordx4 v[170:173], v[248:249], off offset:1024
	s_add_i32 s79, s28, -1
	s_and_b32 s28, s28, s79
	s_add_i32 s79, s29, -1
	s_and_b32 s29, s29, s79
	s_waitcnt vmcnt(4)
	v_lshlrev_b32_e32 v234, 16, v166
	v_and_b32_e32 v235, 0xffff0000, v166
	v_pk_fma_f32 v[226:227], v[230:231], v[234:235], v[226:227] op_sel_hi:[0,1,1]
	v_lshlrev_b32_e32 v238, 16, v167
	v_and_b32_e32 v239, 0xffff0000, v167
	v_pk_fma_f32 v[224:225], v[230:231], v[238:239], v[224:225] op_sel_hi:[0,1,1]
	v_lshlrev_b32_e32 v244, 16, v168
	v_and_b32_e32 v245, 0xffff0000, v168
	v_pk_fma_f32 v[218:219], v[230:231], v[244:245], v[218:219] op_sel_hi:[0,1,1]
	v_lshlrev_b32_e32 v246, 16, v169
	v_and_b32_e32 v247, 0xffff0000, v169
	v_pk_fma_f32 v[216:217], v[230:231], v[246:247], v[216:217] op_sel_hi:[0,1,1]
	v_lshlrev_b32_e32 v234, 16, v162
	v_and_b32_e32 v235, 0xffff0000, v162
	v_pk_fma_f32 v[210:211], v[230:231], v[234:235], v[210:211] op_sel_hi:[0,1,1]
	v_lshlrev_b32_e32 v238, 16, v163
	v_and_b32_e32 v239, 0xffff0000, v163
	v_pk_fma_f32 v[208:209], v[230:231], v[238:239], v[208:209] op_sel_hi:[0,1,1]
	v_lshlrev_b32_e32 v244, 16, v164
	v_and_b32_e32 v245, 0xffff0000, v164
	v_pk_fma_f32 v[202:203], v[230:231], v[244:245], v[202:203] op_sel_hi:[0,1,1]
	v_lshlrev_b32_e32 v246, 16, v165
	v_and_b32_e32 v247, 0xffff0000, v165
	v_pk_fma_f32 v[200:201], v[230:231], v[246:247], v[200:201] op_sel_hi:[0,1,1]
	v_lshlrev_b32_e32 v234, 16, v158
	v_and_b32_e32 v235, 0xffff0000, v158
	v_pk_fma_f32 v[222:223], v[228:229], v[234:235], v[222:223] op_sel_hi:[0,1,1]
	v_lshlrev_b32_e32 v238, 16, v159
	v_and_b32_e32 v239, 0xffff0000, v159
	v_pk_fma_f32 v[220:221], v[228:229], v[238:239], v[220:221] op_sel_hi:[0,1,1]
	v_lshlrev_b32_e32 v244, 16, v160
	v_and_b32_e32 v245, 0xffff0000, v160
	v_pk_fma_f32 v[214:215], v[228:229], v[244:245], v[214:215] op_sel_hi:[0,1,1]
	v_lshlrev_b32_e32 v246, 16, v161
	v_and_b32_e32 v247, 0xffff0000, v161
	v_pk_fma_f32 v[212:213], v[228:229], v[246:247], v[212:213] op_sel_hi:[0,1,1]
	v_lshlrev_b32_e32 v234, 16, v154
	v_and_b32_e32 v235, 0xffff0000, v154
	v_pk_fma_f32 v[206:207], v[228:229], v[234:235], v[206:207] op_sel_hi:[0,1,1]
	v_lshlrev_b32_e32 v238, 16, v155
	v_and_b32_e32 v239, 0xffff0000, v155
	v_pk_fma_f32 v[204:205], v[228:229], v[238:239], v[204:205] op_sel_hi:[0,1,1]
	v_lshlrev_b32_e32 v244, 16, v156
	v_and_b32_e32 v245, 0xffff0000, v156
	v_pk_fma_f32 v[198:199], v[228:229], v[244:245], v[198:199] op_sel_hi:[0,1,1]
	v_lshlrev_b32_e32 v246, 16, v157
	v_and_b32_e32 v247, 0xffff0000, v157
	v_pk_fma_f32 v[196:197], v[228:229], v[246:247], v[196:197] op_sel_hi:[0,1,1]
	s_or_b32 s79, s28, s29
	s_cmp_eq_u32 s79, 0
	s_cbranch_scc1 .Lcmb_last1
	s_ff1_i32_b32 s68, s28
	s_ff1_i32_b32 s69, s29
	s_cmp_eq_u32 s28, 0
	s_cselect_b32 s68, 0, s68
	s_cselect_b64 s[70:71], -1, 0
	s_cmp_eq_u32 s29, 0
	s_cselect_b32 s69, 0, s69
	s_cselect_b64 s[72:73], -1, 0
	s_add_i32 s74, s69, 16
	s_nop 1
	v_readlane_b32 s75, v243, s68
	v_readlane_b32 s76, v242, s68
	v_readlane_b32 s77, v242, s74
	v_readlane_b32 s78, v243, s74
	s_mulk_i32 s68, 0x1200
	s_mulk_i32 s69, 0x1200
	v_mov_b32_e32 v230, s75
	v_mov_b32_e32 v228, s78
	s_cmp_eq_u32 s28, 0
	s_cselect_b32 s76, 0, s76
	s_cmp_eq_u32 s29, 0
	s_cselect_b32 s77, 0, s77
	v_cndmask_b32_e64 v230, v230, 0, s[70:71]
	v_cndmask_b32_e64 v228, v228, 0, s[72:73]
	s_add_i32 s50, s68, s27
	s_add_i32 s50, s50, s76
	s_lshl_b32 s50, s50, 11
	s_mov_b32 s51, 0
	s_add_i32 s54, s69, s27
	s_add_i32 s54, s54, s77
	s_lshl_b32 s54, s54, 11
	s_mov_b32 s55, 0
	v_lshl_add_u64 v[248:249], v[192:193], 0, s[50:51]
	global_load_dwordx4 v[166:169], v[248:249], off
	global_load_dwordx4 v[162:165], v[248:249], off offset:1024
	v_lshl_add_u64 v[248:249], v[192:193], 0, s[54:55]
	global_load_dwordx4 v[158:161], v[248:249], off
	global_load_dwordx4 v[154:157], v[248:249], off offset:1024
	s_add_i32 s79, s28, -1
	s_and_b32 s28, s28, s79
	s_add_i32 s79, s29, -1
	s_and_b32 s29, s29, s79
	s_waitcnt vmcnt(4)
	v_lshlrev_b32_e32 v234, 16, v182
	v_and_b32_e32 v235, 0xffff0000, v182
	v_pk_fma_f32 v[226:227], v[250:251], v[234:235], v[226:227] op_sel_hi:[0,1,1]
	v_lshlrev_b32_e32 v238, 16, v183
	v_and_b32_e32 v239, 0xffff0000, v183
	v_pk_fma_f32 v[224:225], v[250:251], v[238:239], v[224:225] op_sel_hi:[0,1,1]
	v_lshlrev_b32_e32 v244, 16, v184
	v_and_b32_e32 v245, 0xffff0000, v184
	v_pk_fma_f32 v[218:219], v[250:251], v[244:245], v[218:219] op_sel_hi:[0,1,1]
	v_lshlrev_b32_e32 v246, 16, v185
	v_and_b32_e32 v247, 0xffff0000, v185
	v_pk_fma_f32 v[216:217], v[250:251], v[246:247], v[216:217] op_sel_hi:[0,1,1]
	v_lshlrev_b32_e32 v234, 16, v178
	v_and_b32_e32 v235, 0xffff0000, v178
	v_pk_fma_f32 v[210:211], v[250:251], v[234:235], v[210:211] op_sel_hi:[0,1,1]
	v_lshlrev_b32_e32 v238, 16, v179
	v_and_b32_e32 v239, 0xffff0000, v179
	v_pk_fma_f32 v[208:209], v[250:251], v[238:239], v[208:209] op_sel_hi:[0,1,1]
	v_lshlrev_b32_e32 v244, 16, v180
	v_and_b32_e32 v245, 0xffff0000, v180
	v_pk_fma_f32 v[202:203], v[250:251], v[244:245], v[202:203] op_sel_hi:[0,1,1]
	v_lshlrev_b32_e32 v246, 16, v181
	v_and_b32_e32 v247, 0xffff0000, v181
	v_pk_fma_f32 v[200:201], v[250:251], v[246:247], v[200:201] op_sel_hi:[0,1,1]
	v_lshlrev_b32_e32 v234, 16, v174
	v_and_b32_e32 v235, 0xffff0000, v174
	v_pk_fma_f32 v[222:223], v[252:253], v[234:235], v[222:223] op_sel_hi:[0,1,1]
	v_lshlrev_b32_e32 v238, 16, v175
	v_and_b32_e32 v239, 0xffff0000, v175
	v_pk_fma_f32 v[220:221], v[252:253], v[238:239], v[220:221] op_sel_hi:[0,1,1]
	v_lshlrev_b32_e32 v244, 16, v176
	v_and_b32_e32 v245, 0xffff0000, v176
	v_pk_fma_f32 v[214:215], v[252:253], v[244:245], v[214:215] op_sel_hi:[0,1,1]
	v_lshlrev_b32_e32 v246, 16, v177
	v_and_b32_e32 v247, 0xffff0000, v177
	v_pk_fma_f32 v[212:213], v[252:253], v[246:247], v[212:213] op_sel_hi:[0,1,1]
	v_lshlrev_b32_e32 v234, 16, v170
	v_and_b32_e32 v235, 0xffff0000, v170
	v_pk_fma_f32 v[206:207], v[252:253], v[234:235], v[206:207] op_sel_hi:[0,1,1]
	v_lshlrev_b32_e32 v238, 16, v171
	v_and_b32_e32 v239, 0xffff0000, v171
	v_pk_fma_f32 v[204:205], v[252:253], v[238:239], v[204:205] op_sel_hi:[0,1,1]
	v_lshlrev_b32_e32 v244, 16, v172
	v_and_b32_e32 v245, 0xffff0000, v172
	v_pk_fma_f32 v[198:199], v[252:253], v[244:245], v[198:199] op_sel_hi:[0,1,1]
	v_lshlrev_b32_e32 v246, 16, v173
	v_and_b32_e32 v247, 0xffff0000, v173
	v_pk_fma_f32 v[196:197], v[252:253], v[246:247], v[196:197] op_sel_hi:[0,1,1]
	s_branch .Lcmb_loop
.Lcmb_last0:
	s_waitcnt vmcnt(0)
	v_lshlrev_b32_e32 v234, 16, v166
	v_and_b32_e32 v235, 0xffff0000, v166
	v_pk_fma_f32 v[226:227], v[230:231], v[234:235], v[226:227] op_sel_hi:[0,1,1]
	v_lshlrev_b32_e32 v238, 16, v167
	v_and_b32_e32 v239, 0xffff0000, v167
	v_pk_fma_f32 v[224:225], v[230:231], v[238:239], v[224:225] op_sel_hi:[0,1,1]
	v_lshlrev_b32_e32 v244, 16, v168
	v_and_b32_e32 v245, 0xffff0000, v168
	v_pk_fma_f32 v[218:219], v[230:231], v[244:245], v[218:219] op_sel_hi:[0,1,1]
	v_lshlrev_b32_e32 v246, 16, v169
	v_and_b32_e32 v247, 0xffff0000, v169
	v_pk_fma_f32 v[216:217], v[230:231], v[246:247], v[216:217] op_sel_hi:[0,1,1]
	v_lshlrev_b32_e32 v234, 16, v162
	v_and_b32_e32 v235, 0xffff0000, v162
	v_pk_fma_f32 v[210:211], v[230:231], v[234:235], v[210:211] op_sel_hi:[0,1,1]
	v_lshlrev_b32_e32 v238, 16, v163
	v_and_b32_e32 v239, 0xffff0000, v163
	v_pk_fma_f32 v[208:209], v[230:231], v[238:239], v[208:209] op_sel_hi:[0,1,1]
	v_lshlrev_b32_e32 v244, 16, v164
	v_and_b32_e32 v245, 0xffff0000, v164
	v_pk_fma_f32 v[202:203], v[230:231], v[244:245], v[202:203] op_sel_hi:[0,1,1]
	v_lshlrev_b32_e32 v246, 16, v165
	v_and_b32_e32 v247, 0xffff0000, v165
	v_pk_fma_f32 v[200:201], v[230:231], v[246:247], v[200:201] op_sel_hi:[0,1,1]
	v_lshlrev_b32_e32 v234, 16, v158
	v_and_b32_e32 v235, 0xffff0000, v158
	v_pk_fma_f32 v[222:223], v[228:229], v[234:235], v[222:223] op_sel_hi:[0,1,1]
	v_lshlrev_b32_e32 v238, 16, v159
	v_and_b32_e32 v239, 0xffff0000, v159
	v_pk_fma_f32 v[220:221], v[228:229], v[238:239], v[220:221] op_sel_hi:[0,1,1]
	v_lshlrev_b32_e32 v244, 16, v160
	v_and_b32_e32 v245, 0xffff0000, v160
	v_pk_fma_f32 v[214:215], v[228:229], v[244:245], v[214:215] op_sel_hi:[0,1,1]
	v_lshlrev_b32_e32 v246, 16, v161
	v_and_b32_e32 v247, 0xffff0000, v161
	v_pk_fma_f32 v[212:213], v[228:229], v[246:247], v[212:213] op_sel_hi:[0,1,1]
	v_lshlrev_b32_e32 v234, 16, v154
	v_and_b32_e32 v235, 0xffff0000, v154
	v_pk_fma_f32 v[206:207], v[228:229], v[234:235], v[206:207] op_sel_hi:[0,1,1]
	v_lshlrev_b32_e32 v238, 16, v155
	v_and_b32_e32 v239, 0xffff0000, v155
	v_pk_fma_f32 v[204:205], v[228:229], v[238:239], v[204:205] op_sel_hi:[0,1,1]
	v_lshlrev_b32_e32 v244, 16, v156
	v_and_b32_e32 v245, 0xffff0000, v156
	v_pk_fma_f32 v[198:199], v[228:229], v[244:245], v[198:199] op_sel_hi:[0,1,1]
	v_lshlrev_b32_e32 v246, 16, v157
	v_and_b32_e32 v247, 0xffff0000, v157
	v_pk_fma_f32 v[196:197], v[228:229], v[246:247], v[196:197] op_sel_hi:[0,1,1]
	s_branch .Lcmb_done
.Lcmb_last1:
	s_waitcnt vmcnt(0)
	v_lshlrev_b32_e32 v234, 16, v182
	v_and_b32_e32 v235, 0xffff0000, v182
	v_pk_fma_f32 v[226:227], v[250:251], v[234:235], v[226:227] op_sel_hi:[0,1,1]
	v_lshlrev_b32_e32 v238, 16, v183
	v_and_b32_e32 v239, 0xffff0000, v183
	v_pk_fma_f32 v[224:225], v[250:251], v[238:239], v[224:225] op_sel_hi:[0,1,1]
	v_lshlrev_b32_e32 v244, 16, v184
	v_and_b32_e32 v245, 0xffff0000, v184
	v_pk_fma_f32 v[218:219], v[250:251], v[244:245], v[218:219] op_sel_hi:[0,1,1]
	v_lshlrev_b32_e32 v246, 16, v185
	v_and_b32_e32 v247, 0xffff0000, v185
	v_pk_fma_f32 v[216:217], v[250:251], v[246:247], v[216:217] op_sel_hi:[0,1,1]
	v_lshlrev_b32_e32 v234, 16, v178
	v_and_b32_e32 v235, 0xffff0000, v178
	v_pk_fma_f32 v[210:211], v[250:251], v[234:235], v[210:211] op_sel_hi:[0,1,1]
	v_lshlrev_b32_e32 v238, 16, v179
	v_and_b32_e32 v239, 0xffff0000, v179
	v_pk_fma_f32 v[208:209], v[250:251], v[238:239], v[208:209] op_sel_hi:[0,1,1]
	v_lshlrev_b32_e32 v244, 16, v180
	v_and_b32_e32 v245, 0xffff0000, v180
	v_pk_fma_f32 v[202:203], v[250:251], v[244:245], v[202:203] op_sel_hi:[0,1,1]
	v_lshlrev_b32_e32 v246, 16, v181
	v_and_b32_e32 v247, 0xffff0000, v181
	v_pk_fma_f32 v[200:201], v[250:251], v[246:247], v[200:201] op_sel_hi:[0,1,1]
	v_lshlrev_b32_e32 v234, 16, v174
	v_and_b32_e32 v235, 0xffff0000, v174
	v_pk_fma_f32 v[222:223], v[252:253], v[234:235], v[222:223] op_sel_hi:[0,1,1]
	v_lshlrev_b32_e32 v238, 16, v175
	v_and_b32_e32 v239, 0xffff0000, v175
	v_pk_fma_f32 v[220:221], v[252:253], v[238:239], v[220:221] op_sel_hi:[0,1,1]
	v_lshlrev_b32_e32 v244, 16, v176
	v_and_b32_e32 v245, 0xffff0000, v176
	v_pk_fma_f32 v[214:215], v[252:253], v[244:245], v[214:215] op_sel_hi:[0,1,1]
	v_lshlrev_b32_e32 v246, 16, v177
	v_and_b32_e32 v247, 0xffff0000, v177
	v_pk_fma_f32 v[212:213], v[252:253], v[246:247], v[212:213] op_sel_hi:[0,1,1]
	v_lshlrev_b32_e32 v234, 16, v170
	v_and_b32_e32 v235, 0xffff0000, v170
	v_pk_fma_f32 v[206:207], v[252:253], v[234:235], v[206:207] op_sel_hi:[0,1,1]
	v_lshlrev_b32_e32 v238, 16, v171
	v_and_b32_e32 v239, 0xffff0000, v171
	v_pk_fma_f32 v[204:205], v[252:253], v[238:239], v[204:205] op_sel_hi:[0,1,1]
	v_lshlrev_b32_e32 v244, 16, v172
	v_and_b32_e32 v245, 0xffff0000, v172
	v_pk_fma_f32 v[198:199], v[252:253], v[244:245], v[198:199] op_sel_hi:[0,1,1]
	v_lshlrev_b32_e32 v246, 16, v173
	v_and_b32_e32 v247, 0xffff0000, v173
	v_pk_fma_f32 v[196:197], v[252:253], v[246:247], v[196:197] op_sel_hi:[0,1,1]
.Lcmb_done:
	ds_read_b128 v[170:173], v254
	ds_read_b128 v[174:177], v254 offset:8192
	ds_read_b128 v[178:181], v254 offset:16384
	ds_read_b128 v[182:185], v254 offset:24576
	s_waitcnt lgkmcnt(0)
	s_branch .LBB0_1628
